# scan loaders issue one chunk further ahead (13-14 instead of 12-13): ten chunks in flight
# baseline (speedup 1.0000x reference)
; #define SP_BAR() asm volatile("s_waitcnt lgkmcnt(0)\n\ts_barrier" ::: "memory")
; #define SP_WAIT() asm volatile("s_waitcnt vmcnt(36)" ::: "memory")
; __device__ __forceinline__ void p3_rwkv_state(Frame& F, const Args& a) {
;     ...
;     if (loader) {
;         DmaPtrs P; rw_dma_init(a, P, head, ib, lw, lane);
;         for (int n = 0; n < SP_D; ++n) rw_dma_issue(P, lw, lane, lds0 + (unsigned)(n % SP_R) * SP_SLOT);
;         SP_WAIT();
;         SP_BAR();
.Lscan_ldbig_pro:
	s_add_i32 s16, s15, s14
	s_mov_b32 m0, s16
	s_add_i32 s15, s15, 0x2800
	global_load_lds_dwordx4 v[2:3], off
	global_load_lds_dwordx4 v[2:3], off offset:1024
	s_cmp_eq_u32 s15, 0x25800
	s_cselect_b32 s15, 0, s15
	v_lshl_add_u64 v[2:3], v[2:3], 0, s[6:7]
	s_add_i32 s18, s18, 1
	s_cmp_lt_u32 s18, 13
	s_cbranch_scc1 .Lscan_ldbig_pro
	s_waitcnt vmcnt(20)
	s_barrier
	s_mov_b32 s18, 0
	s_movk_i32 s17, 0x100

; #define SP_BAR() asm volatile("s_waitcnt lgkmcnt(0)\n\ts_barrier" ::: "memory")
; #define SP_WAIT() asm volatile("s_waitcnt vmcnt(36)" ::: "memory")
; __device__ __forceinline__ void p3_rwkv_state(Frame& F, const Args& a) {
;     ...
;         for (int n = 0; n < NC; n += 2) {
;             if (n + SP_D + 1 < NC) { rw_dma_issue(P, lw, lane, lds0 + (unsigned)((n + SP_D) % SP_R) * SP_SLOT); rw_dma_issue(P, lw, lane, lds0 + (unsigned)((n + SP_D + 1) % SP_R) * SP_SLOT); SP_WAIT(); }
;             else asm volatile("s_waitcnt vmcnt(0)" ::: "memory");
;             SP_BAR();
.Lscan_ldbig_chk:
	s_lshr_b32 s24, s18, 1
	s_add_i32 s24, s24, 7
	s_cmp_lt_u32 s24, s17
	s_cbranch_scc1 .Lscan_ldbig_go
	v_add_u32_e32 v12, s17, v76
	v_lshlrev_b32_e32 v13, 2, v12
	v_add_u32_e32 v13, 0x8000, v13
	global_load_dword v13, v13, s[90:91] sc1
	s_movk_i32 s24, 0x1ff
	s_waitcnt vmcnt(0)
	v_cmp_ne_u32_e64 s[20:21], 0, v13
	v_cmp_lt_u32_e64 s[22:23], s24, v12
	s_nop 1
	s_or_b64 s[20:21], s[20:21], s[22:23]
	s_not_b64 s[20:21], s[20:21]
	s_ff1_i32_b64 s24, s[20:21]
	s_cmp_eq_u32 s24, -1
	s_cselect_b32 s24, 64, s24
	s_add_i32 s17, s17, s24
	s_cmp_lg_u32 s24, 0
	s_cbranch_scc1 .Lscan_ldbig_chk
	s_sleep 8
	s_branch .Lscan_ldbig_chk
.Lscan_ldbig_go:
	s_add_i32 s16, s15, s14
	s_mov_b32 m0, s16
	s_add_i32 s15, s15, 0x2800
	global_load_lds_dwordx4 v[2:3], off
	global_load_lds_dwordx4 v[2:3], off offset:1024
	s_cmp_eq_u32 s15, 0x25800
	s_cselect_b32 s15, 0, s15
	v_lshl_add_u64 v[2:3], v[2:3], 0, s[6:7]
	s_cmpk_eq_u32 s18, 0x3f2
	s_cbranch_scc1 .Lscan_ldbig_one
	s_add_i32 s16, s15, s14
	s_mov_b32 m0, s16
	s_add_i32 s15, s15, 0x2800
	global_load_lds_dwordx4 v[2:3], off
	global_load_lds_dwordx4 v[2:3], off offset:1024
	s_cmp_eq_u32 s15, 0x25800
	s_cselect_b32 s15, 0, s15
	v_lshl_add_u64 v[2:3], v[2:3], 0, s[6:7]
.Lscan_ldbig_one:
	s_waitcnt vmcnt(20)
	s_branch .Lscan_ldbig_bar

; #define SP_BAR() asm volatile("s_waitcnt lgkmcnt(0)\n\ts_barrier" ::: "memory")
; #define SP_WAIT() asm volatile("s_waitcnt vmcnt(36)" ::: "memory")
; __device__ __forceinline__ void p3_rwkv_state(Frame& F, const Args& a) {
;     ...
;     if (loader) {
;         DmaPtrs P; rw_dma_init(a, P, head, ib, lw, lane);
;         for (int n = 0; n < SP_D; ++n) rw_dma_issue(P, lw, lane, lds0 + (unsigned)(n % SP_R) * SP_SLOT);
;         SP_WAIT();
;         SP_BAR();
.Lscan_ldsmall_pro:
	s_add_i32 s16, s15, 0x2000
	s_mov_b32 m0, s16
	s_mov_b32 exec_hi, 0
	s_add_i32 s15, s15, 0x2800
	global_load_lds_dwordx4 v[2:3], off
	global_load_lds_dwordx4 v[4:5], off offset:512
	global_load_lds_dwordx4 v[6:7], off offset:1024
	s_mov_b32 exec_lo, 0xffff
	s_cmp_eq_u32 s15, 0x25800
	global_load_lds_dwordx4 v[8:9], off offset:1536
	s_mov_b64 exec, -1
	s_cselect_b32 s15, 0, s15
	v_lshl_add_u64 v[2:3], v[2:3], 0, s[6:7]
	v_lshl_add_u64 v[4:5], v[4:5], 0, s[6:7]
	v_lshl_add_u64 v[6:7], v[6:7], 0, s[6:7]
	v_lshl_add_u64 v[8:9], v[8:9], 0, s[10:11]
	s_add_i32 s18, s18, 1
	s_cmp_lt_u32 s18, 13
	s_cbranch_scc1 .Lscan_ldsmall_pro
	s_waitcnt vmcnt(40)
	s_barrier
	s_mov_b32 s18, 0
	s_movk_i32 s17, 0x100

; #define SP_BAR() asm volatile("s_waitcnt lgkmcnt(0)\n\ts_barrier" ::: "memory")
; #define SP_WAIT() asm volatile("s_waitcnt vmcnt(36)" ::: "memory")
; __device__ __forceinline__ void p3_rwkv_state(Frame& F, const Args& a) {
;     ...
;         for (int n = 0; n < NC; n += 2) {
;             if (n + SP_D + 1 < NC) { rw_dma_issue(P, lw, lane, lds0 + (unsigned)((n + SP_D) % SP_R) * SP_SLOT); rw_dma_issue(P, lw, lane, lds0 + (unsigned)((n + SP_D + 1) % SP_R) * SP_SLOT); SP_WAIT(); }
;             else asm volatile("s_waitcnt vmcnt(0)" ::: "memory");
;             SP_BAR();
.Lscan_ldsmall_go:
	s_add_i32 s16, s15, 0x2000
	s_mov_b32 m0, s16
	s_mov_b32 exec_hi, 0
	s_add_i32 s15, s15, 0x2800
	global_load_lds_dwordx4 v[2:3], off
	global_load_lds_dwordx4 v[4:5], off offset:512
	global_load_lds_dwordx4 v[6:7], off offset:1024
	s_mov_b32 exec_lo, 0xffff
	s_cmp_eq_u32 s15, 0x25800
	global_load_lds_dwordx4 v[8:9], off offset:1536
	s_mov_b64 exec, -1
	s_cselect_b32 s15, 0, s15
	v_lshl_add_u64 v[2:3], v[2:3], 0, s[6:7]
	v_lshl_add_u64 v[4:5], v[4:5], 0, s[6:7]
	v_lshl_add_u64 v[6:7], v[6:7], 0, s[6:7]
	v_lshl_add_u64 v[8:9], v[8:9], 0, s[10:11]
	s_cmpk_eq_u32 s18, 0x3f2
	s_cbranch_scc1 .Lscan_ldsmall_one
	s_add_i32 s16, s15, 0x2000
	s_mov_b32 m0, s16
	s_mov_b32 exec_hi, 0
	s_add_i32 s15, s15, 0x2800
	global_load_lds_dwordx4 v[2:3], off
	global_load_lds_dwordx4 v[4:5], off offset:512
	global_load_lds_dwordx4 v[6:7], off offset:1024
	s_mov_b32 exec_lo, 0xffff
	s_cmp_eq_u32 s15, 0x25800
	global_load_lds_dwordx4 v[8:9], off offset:1536
	s_mov_b64 exec, -1
	s_cselect_b32 s15, 0, s15
	v_lshl_add_u64 v[2:3], v[2:3], 0, s[6:7]
	v_lshl_add_u64 v[4:5], v[4:5], 0, s[6:7]
	v_lshl_add_u64 v[6:7], v[6:7], 0, s[6:7]
	v_lshl_add_u64 v[8:9], v[8:9], 0, s[10:11]
.Lscan_ldsmall_one:
	s_waitcnt vmcnt(40)
	s_branch .Lscan_ldsmall_bar
